# EpiResid (down, w_out): second-half residual rows prefetched into L1 (scratch quad) together with the first half's loads; on top of v_micro6
# baseline (speedup 1.0000x reference)
.LBB0_438:
	v_lshl_or_b32 v140, s27, 8, v204
	v_lshl_add_u32 v144, s26, 8, v202
	s_lshl_b64 s[26:27], s[28:29], 2
	s_add_u32 s26, s17, s26
	s_addc_u32 s27, s71, s27
	v_ashrrev_i32_e32 v141, 31, v140
	v_lshl_add_u64 v[142:143], v[140:141], 2, s[26:27]
	global_load_dwordx4 v[178:181], v[142:143], off offset:16
	global_load_dwordx4 v[182:185], v[142:143], off
	global_load_dwordx4 v[170:173], v[142:143], off offset:528
	global_load_dwordx4 v[174:177], v[142:143], off offset:512
	v_lshlrev_b64 v[186:187], 1, v[140:141]
	v_ashrrev_i32_e32 v145, 31, v144
	v_lshl_add_u64 v[188:189], s[10:11], 0, v[186:187]
	v_lshlrev_b64 v[190:191], 12, v[144:145]
	s_mov_b64 s[26:27], 0x80000
	s_andn2_b64 vcc, exec, s[4:5]
	v_lshl_add_u64 v[132:133], v[188:189], 0, v[190:191]
	v_lshl_add_u64 v[250:251], v[132:133], 0, s[26:27]
	global_load_dwordx4 v[244:247], v[250:251], off
	global_load_dwordx4 v[244:247], v[250:251], off offset:256
	global_load_dwordx4 v[206:209], v[132:133], off
	global_load_dwordx4 v[156:159], v[132:133], off offset:256
	v_or_b32_e32 v132, 16, v144
	v_ashrrev_i32_e32 v133, 31, v132
	v_lshlrev_b64 v[200:201], 12, v[132:133]
	v_lshl_add_u64 v[132:133], v[188:189], 0, v[200:201]
	v_lshl_add_u64 v[250:251], v[132:133], 0, s[26:27]
	global_load_dwordx4 v[244:247], v[250:251], off
	global_load_dwordx4 v[244:247], v[250:251], off offset:256
	global_load_dwordx4 v[152:155], v[132:133], off
	global_load_dwordx4 v[148:151], v[132:133], off offset:256
	v_or_b32_e32 v132, 32, v144
	v_ashrrev_i32_e32 v133, 31, v132
	v_lshlrev_b64 v[192:193], 12, v[132:133]
	v_lshl_add_u64 v[132:133], v[188:189], 0, v[192:193]
	v_lshl_add_u64 v[250:251], v[132:133], 0, s[26:27]
	global_load_dwordx4 v[244:247], v[250:251], off
	global_load_dwordx4 v[244:247], v[250:251], off offset:256
	global_load_dwordx4 v[140:143], v[132:133], off
	s_nop 0
	global_load_dwordx4 v[132:135], v[132:133], off offset:256
	v_or_b32_e32 v136, 48, v144
	v_ashrrev_i32_e32 v137, 31, v136
	v_lshlrev_b64 v[194:195], 12, v[136:137]
	v_lshl_add_u64 v[136:137], v[188:189], 0, v[194:195]
	v_lshl_add_u64 v[250:251], v[136:137], 0, s[26:27]
	global_load_dwordx4 v[244:247], v[250:251], off
	global_load_dwordx4 v[244:247], v[250:251], off offset:256
	global_load_dwordx4 v[144:147], v[136:137], off
	s_nop 0
	global_load_dwordx4 v[136:139], v[136:137], off offset:256
	s_waitcnt vmcnt(0)
	v_pk_mul_f32 v[170:171], v[170:171], 0.5 op_sel_hi:[1,0]
	v_pk_mul_f32 v[172:173], v[172:173], 0.5 op_sel_hi:[1,0]
	v_pk_mul_f32 v[174:175], v[174:175], 0.5 op_sel_hi:[1,0]
	v_pk_mul_f32 v[176:177], v[176:177], 0.5 op_sel_hi:[1,0]
	v_pk_mul_f32 v[178:179], v[178:179], 0.5 op_sel_hi:[1,0]
	v_pk_mul_f32 v[180:181], v[180:181], 0.5 op_sel_hi:[1,0]
	v_pk_mul_f32 v[182:183], v[182:183], 0.5 op_sel_hi:[1,0]
	v_pk_mul_f32 v[184:185], v[184:185], 0.5 op_sel_hi:[1,0]
	s_waitcnt vmcnt(7)
	v_lshlrev_b32_e32 v210, 16, v206
	v_and_b32_e32 v211, 0xffff0000, v206
	v_lshlrev_b32_e32 v206, 16, v207
	v_and_b32_e32 v207, 0xffff0000, v207
	v_pk_fma_f32 v[130:131], v[130:131], v[184:185], v[206:207]
	v_pk_fma_f32 v[128:129], v[128:129], v[182:183], v[210:211]
	v_lshlrev_b32_e32 v206, 16, v208
	v_and_b32_e32 v207, 0xffff0000, v208
	v_lshlrev_b32_e32 v208, 16, v209
	v_and_b32_e32 v209, 0xffff0000, v209
	v_pk_fma_f32 v[208:209], v[126:127], v[180:181], v[208:209]
	v_pk_fma_f32 v[126:127], v[124:125], v[178:179], v[206:207]
	v_cvt_pk_bf16_f32 v124, v128, v129
	v_lshl_add_u64 v[128:129], s[10:11], 0, v[190:191]
	v_cvt_pk_bf16_f32 v125, v130, v131
	v_cvt_pk_bf16_f32 v126, v126, v127
	v_cvt_pk_bf16_f32 v127, v208, v209
	v_lshl_add_u64 v[128:129], v[128:129], 0, v[186:187]
	global_store_dwordx4 v[128:129], v[124:127], off
	s_waitcnt vmcnt(7)
	s_nop 0
	v_lshlrev_b32_e32 v124, 16, v156
	v_and_b32_e32 v125, 0xffff0000, v156
	v_lshlrev_b32_e32 v126, 16, v157
	v_and_b32_e32 v127, 0xffff0000, v157
	v_pk_fma_f32 v[122:123], v[122:123], v[176:177], v[126:127]
	v_pk_fma_f32 v[120:121], v[120:121], v[174:175], v[124:125]
	v_lshlrev_b32_e32 v124, 16, v158
	v_and_b32_e32 v125, 0xffff0000, v158
	v_lshlrev_b32_e32 v126, 16, v159
	v_and_b32_e32 v127, 0xffff0000, v159
	v_pk_fma_f32 v[126:127], v[118:119], v[172:173], v[126:127]
	v_pk_fma_f32 v[118:119], v[116:117], v[170:171], v[124:125]
	v_cvt_pk_bf16_f32 v116, v120, v121
	v_cvt_pk_bf16_f32 v117, v122, v123
	s_nop 0
	v_cvt_pk_bf16_f32 v118, v118, v119
	v_cvt_pk_bf16_f32 v119, v126, v127
	global_store_dwordx4 v[128:129], v[116:119], off offset:256
	s_waitcnt vmcnt(7)
	s_nop 0
	v_lshlrev_b32_e32 v116, 16, v152
	v_and_b32_e32 v117, 0xffff0000, v152
	v_lshlrev_b32_e32 v118, 16, v153
	v_and_b32_e32 v119, 0xffff0000, v153
	v_pk_fma_f32 v[114:115], v[114:115], v[184:185], v[118:119]
	v_pk_fma_f32 v[112:113], v[112:113], v[182:183], v[116:117]
	v_lshlrev_b32_e32 v116, 16, v154
	v_and_b32_e32 v117, 0xffff0000, v154
	v_lshlrev_b32_e32 v118, 16, v155
	v_and_b32_e32 v119, 0xffff0000, v155
	v_pk_fma_f32 v[118:119], v[110:111], v[180:181], v[118:119]
	v_pk_fma_f32 v[110:111], v[108:109], v[178:179], v[116:117]
	v_cvt_pk_bf16_f32 v108, v112, v113
	v_lshl_add_u64 v[112:113], s[10:11], 0, v[200:201]
	v_cvt_pk_bf16_f32 v109, v114, v115
	v_cvt_pk_bf16_f32 v110, v110, v111
	v_cvt_pk_bf16_f32 v111, v118, v119
	v_lshl_add_u64 v[112:113], v[112:113], 0, v[186:187]
	global_store_dwordx4 v[112:113], v[108:111], off
	s_waitcnt vmcnt(7)
	s_nop 0
	v_lshlrev_b32_e32 v108, 16, v148
	v_and_b32_e32 v109, 0xffff0000, v148
	v_lshlrev_b32_e32 v110, 16, v149
	v_and_b32_e32 v111, 0xffff0000, v149
	v_pk_fma_f32 v[106:107], v[106:107], v[176:177], v[110:111]
	v_pk_fma_f32 v[104:105], v[104:105], v[174:175], v[108:109]
	v_lshlrev_b32_e32 v108, 16, v150
	v_and_b32_e32 v109, 0xffff0000, v150
	v_lshlrev_b32_e32 v110, 16, v151
	v_and_b32_e32 v111, 0xffff0000, v151
	v_pk_fma_f32 v[110:111], v[102:103], v[172:173], v[110:111]
	v_pk_fma_f32 v[102:103], v[100:101], v[170:171], v[108:109]
	v_cvt_pk_bf16_f32 v100, v104, v105
	v_cvt_pk_bf16_f32 v101, v106, v107
	s_nop 0
	v_cvt_pk_bf16_f32 v102, v102, v103
	v_cvt_pk_bf16_f32 v103, v110, v111
	global_store_dwordx4 v[112:113], v[100:103], off offset:256
	s_waitcnt vmcnt(7)
	s_nop 0
	v_lshlrev_b32_e32 v100, 16, v140
	v_and_b32_e32 v101, 0xffff0000, v140
	v_lshlrev_b32_e32 v102, 16, v141
	v_and_b32_e32 v103, 0xffff0000, v141
	v_pk_fma_f32 v[98:99], v[98:99], v[184:185], v[102:103]
	v_pk_fma_f32 v[96:97], v[96:97], v[182:183], v[100:101]
	v_lshlrev_b32_e32 v100, 16, v142
	v_and_b32_e32 v101, 0xffff0000, v142
	v_lshlrev_b32_e32 v102, 16, v143
	v_and_b32_e32 v103, 0xffff0000, v143
	v_pk_fma_f32 v[102:103], v[94:95], v[180:181], v[102:103]
	v_pk_fma_f32 v[94:95], v[92:93], v[178:179], v[100:101]
	v_cvt_pk_bf16_f32 v92, v96, v97
	v_lshl_add_u64 v[96:97], s[10:11], 0, v[192:193]
	v_cvt_pk_bf16_f32 v93, v98, v99
	v_cvt_pk_bf16_f32 v94, v94, v95
	v_cvt_pk_bf16_f32 v95, v102, v103
	v_lshl_add_u64 v[96:97], v[96:97], 0, v[186:187]
	global_store_dwordx4 v[96:97], v[92:95], off
	s_waitcnt vmcnt(7)
	s_nop 0
	v_lshlrev_b32_e32 v92, 16, v132
	v_and_b32_e32 v93, 0xffff0000, v132
	v_lshlrev_b32_e32 v94, 16, v133
	v_and_b32_e32 v95, 0xffff0000, v133
	v_pk_fma_f32 v[86:87], v[86:87], v[176:177], v[94:95]
	v_pk_fma_f32 v[84:85], v[84:85], v[174:175], v[92:93]
	v_lshlrev_b32_e32 v92, 16, v134
	v_and_b32_e32 v93, 0xffff0000, v134
	v_lshlrev_b32_e32 v94, 16, v135
	v_and_b32_e32 v95, 0xffff0000, v135
	v_pk_fma_f32 v[94:95], v[78:79], v[172:173], v[94:95]
	v_pk_fma_f32 v[78:79], v[76:77], v[170:171], v[92:93]
	v_cvt_pk_bf16_f32 v76, v84, v85
	v_cvt_pk_bf16_f32 v77, v86, v87
	s_waitcnt vmcnt(6)
	v_lshlrev_b32_e32 v84, 16, v146
	v_cvt_pk_bf16_f32 v78, v78, v79
	v_cvt_pk_bf16_f32 v79, v94, v95
	global_store_dwordx4 v[96:97], v[76:79], off offset:256
	v_and_b32_e32 v85, 0xffff0000, v146
	v_pk_fma_f32 v[80:81], v[80:81], v[178:179], v[84:85]
	v_lshlrev_b32_e32 v76, 16, v144
	v_and_b32_e32 v77, 0xffff0000, v144
	v_lshlrev_b32_e32 v78, 16, v145
	v_and_b32_e32 v79, 0xffff0000, v145
	v_pk_fma_f32 v[78:79], v[90:91], v[184:185], v[78:79]
	v_pk_fma_f32 v[76:77], v[88:89], v[182:183], v[76:77]
	v_lshlrev_b32_e32 v86, 16, v147
	v_and_b32_e32 v87, 0xffff0000, v147
	v_cvt_pk_bf16_f32 v76, v76, v77
	v_cvt_pk_bf16_f32 v77, v78, v79
	v_cvt_pk_bf16_f32 v78, v80, v81
	v_lshl_add_u64 v[80:81], s[10:11], 0, v[194:195]
	v_pk_fma_f32 v[82:83], v[82:83], v[180:181], v[86:87]
	v_lshl_add_u64 v[80:81], v[80:81], 0, v[186:187]
	v_cvt_pk_bf16_f32 v79, v82, v83
	global_store_dwordx4 v[80:81], v[76:79], off
	v_lshl_add_u64 v[84:85], v[190:191], 0, s[26:27]
	s_mov_b64 s[26:27], 0x90000
	s_waitcnt vmcnt(7)
	v_lshlrev_b32_e32 v76, 16, v136
	v_and_b32_e32 v77, 0xffff0000, v136
	v_lshlrev_b32_e32 v78, 16, v137
	v_and_b32_e32 v79, 0xffff0000, v137
	v_pk_fma_f32 v[74:75], v[74:75], v[176:177], v[78:79]
	v_pk_fma_f32 v[72:73], v[72:73], v[174:175], v[76:77]
	v_lshlrev_b32_e32 v76, 16, v138
	v_and_b32_e32 v77, 0xffff0000, v138
	v_lshlrev_b32_e32 v78, 16, v139
	v_and_b32_e32 v79, 0xffff0000, v139
	v_pk_fma_f32 v[78:79], v[70:71], v[172:173], v[78:79]
	v_pk_fma_f32 v[70:71], v[68:69], v[170:171], v[76:77]
	v_cvt_pk_bf16_f32 v68, v72, v73
	v_cvt_pk_bf16_f32 v69, v74, v75
	v_lshl_add_u64 v[88:89], v[190:191], 0, s[26:27]
	v_cvt_pk_bf16_f32 v70, v70, v71
	v_cvt_pk_bf16_f32 v71, v78, v79
	global_store_dwordx4 v[80:81], v[68:71], off offset:256
	s_mov_b64 s[26:27], 0xa0000
	v_lshl_add_u64 v[106:107], v[190:191], 0, s[26:27]
	v_lshl_add_u64 v[68:69], v[188:189], 0, v[84:85]
	global_load_dwordx4 v[72:75], v[68:69], off
	global_load_dwordx4 v[80:83], v[68:69], off offset:256
	v_lshl_add_u64 v[68:69], v[188:189], 0, v[88:89]
	global_load_dwordx4 v[90:93], v[68:69], off
	global_load_dwordx4 v[94:97], v[68:69], off offset:256
	v_lshl_add_u64 v[68:69], v[188:189], 0, v[106:107]
	global_load_dwordx4 v[98:101], v[68:69], off
	global_load_dwordx4 v[102:105], v[68:69], off offset:256
	s_mov_b64 s[26:27], 0xb0000
	v_lshl_add_u64 v[86:87], v[190:191], 0, s[26:27]
	v_lshl_add_u64 v[68:69], v[188:189], 0, v[86:87]
	global_load_dwordx4 v[76:79], v[68:69], off
	s_nop 0
	global_load_dwordx4 v[68:71], v[68:69], off offset:256
	s_mov_b64 s[26:27], -1
	s_waitcnt vmcnt(7)
	v_lshlrev_b32_e32 v108, 16, v72
	v_and_b32_e32 v109, 0xffff0000, v72
	v_lshlrev_b32_e32 v72, 16, v73
	v_and_b32_e32 v73, 0xffff0000, v73
	v_pk_fma_f32 v[66:67], v[66:67], v[184:185], v[72:73]
	v_pk_fma_f32 v[64:65], v[64:65], v[182:183], v[108:109]
	v_lshlrev_b32_e32 v72, 16, v74
	v_and_b32_e32 v73, 0xffff0000, v74
	v_lshlrev_b32_e32 v74, 16, v75
	v_and_b32_e32 v75, 0xffff0000, v75
	v_pk_fma_f32 v[74:75], v[62:63], v[180:181], v[74:75]
	v_pk_fma_f32 v[62:63], v[60:61], v[178:179], v[72:73]
	v_cvt_pk_bf16_f32 v60, v64, v65
	v_lshl_add_u64 v[64:65], s[10:11], 0, v[84:85]
	v_cvt_pk_bf16_f32 v61, v66, v67
	v_cvt_pk_bf16_f32 v62, v62, v63
	v_cvt_pk_bf16_f32 v63, v74, v75
	v_lshl_add_u64 v[64:65], v[64:65], 0, v[186:187]
	global_store_dwordx4 v[64:65], v[60:63], off
	s_waitcnt vmcnt(7)
	s_nop 0
	v_lshlrev_b32_e32 v60, 16, v80
	v_and_b32_e32 v61, 0xffff0000, v80
	v_lshlrev_b32_e32 v62, 16, v81
	v_and_b32_e32 v63, 0xffff0000, v81
	v_pk_fma_f32 v[58:59], v[58:59], v[176:177], v[62:63]
	v_pk_fma_f32 v[56:57], v[56:57], v[174:175], v[60:61]
	v_lshlrev_b32_e32 v60, 16, v82
	v_and_b32_e32 v61, 0xffff0000, v82
	v_lshlrev_b32_e32 v62, 16, v83
	v_and_b32_e32 v63, 0xffff0000, v83
	v_pk_fma_f32 v[62:63], v[54:55], v[172:173], v[62:63]
	v_pk_fma_f32 v[54:55], v[52:53], v[170:171], v[60:61]
	v_cvt_pk_bf16_f32 v52, v56, v57
	v_cvt_pk_bf16_f32 v53, v58, v59
	s_nop 0
	v_cvt_pk_bf16_f32 v54, v54, v55
	v_cvt_pk_bf16_f32 v55, v62, v63
	global_store_dwordx4 v[64:65], v[52:55], off offset:256
	s_waitcnt vmcnt(7)
	s_nop 0
	v_lshlrev_b32_e32 v52, 16, v90
	v_and_b32_e32 v53, 0xffff0000, v90
	v_lshlrev_b32_e32 v54, 16, v91
	v_and_b32_e32 v55, 0xffff0000, v91
	v_pk_fma_f32 v[50:51], v[50:51], v[184:185], v[54:55]
	v_pk_fma_f32 v[48:49], v[48:49], v[182:183], v[52:53]
	v_lshlrev_b32_e32 v52, 16, v92
	v_and_b32_e32 v53, 0xffff0000, v92
	v_lshlrev_b32_e32 v54, 16, v93
	v_and_b32_e32 v55, 0xffff0000, v93
	v_pk_fma_f32 v[54:55], v[46:47], v[180:181], v[54:55]
	v_pk_fma_f32 v[46:47], v[44:45], v[178:179], v[52:53]
	v_cvt_pk_bf16_f32 v44, v48, v49
	v_lshl_add_u64 v[48:49], s[10:11], 0, v[88:89]
	v_cvt_pk_bf16_f32 v45, v50, v51
	v_cvt_pk_bf16_f32 v46, v46, v47
	v_cvt_pk_bf16_f32 v47, v54, v55
	v_lshl_add_u64 v[48:49], v[48:49], 0, v[186:187]
	global_store_dwordx4 v[48:49], v[44:47], off
	s_waitcnt vmcnt(7)
	s_nop 0
	v_lshlrev_b32_e32 v44, 16, v94
	v_and_b32_e32 v45, 0xffff0000, v94
	v_lshlrev_b32_e32 v46, 16, v95
	v_and_b32_e32 v47, 0xffff0000, v95
	v_pk_fma_f32 v[42:43], v[42:43], v[176:177], v[46:47]
	v_pk_fma_f32 v[40:41], v[40:41], v[174:175], v[44:45]
	v_lshlrev_b32_e32 v44, 16, v96
	v_and_b32_e32 v45, 0xffff0000, v96
	v_lshlrev_b32_e32 v46, 16, v97
	v_and_b32_e32 v47, 0xffff0000, v97
	v_pk_fma_f32 v[46:47], v[38:39], v[172:173], v[46:47]
	v_pk_fma_f32 v[38:39], v[36:37], v[170:171], v[44:45]
	v_cvt_pk_bf16_f32 v36, v40, v41
	v_cvt_pk_bf16_f32 v37, v42, v43
	s_nop 0
	v_cvt_pk_bf16_f32 v38, v38, v39
	v_cvt_pk_bf16_f32 v39, v46, v47
	global_store_dwordx4 v[48:49], v[36:39], off offset:256
	s_waitcnt vmcnt(7)
	s_nop 0
	v_lshlrev_b32_e32 v36, 16, v98
	v_and_b32_e32 v37, 0xffff0000, v98
	v_lshlrev_b32_e32 v38, 16, v99
	v_and_b32_e32 v39, 0xffff0000, v99
	v_pk_fma_f32 v[34:35], v[34:35], v[184:185], v[38:39]
	v_pk_fma_f32 v[32:33], v[32:33], v[182:183], v[36:37]
	v_lshlrev_b32_e32 v36, 16, v100
	v_and_b32_e32 v37, 0xffff0000, v100
	v_lshlrev_b32_e32 v38, 16, v101
	v_and_b32_e32 v39, 0xffff0000, v101
	v_pk_fma_f32 v[38:39], v[30:31], v[180:181], v[38:39]
	v_pk_fma_f32 v[30:31], v[28:29], v[178:179], v[36:37]
	v_cvt_pk_bf16_f32 v28, v32, v33
	v_lshl_add_u64 v[32:33], s[10:11], 0, v[106:107]
	v_cvt_pk_bf16_f32 v29, v34, v35
	v_cvt_pk_bf16_f32 v30, v30, v31
	v_cvt_pk_bf16_f32 v31, v38, v39
	v_lshl_add_u64 v[32:33], v[32:33], 0, v[186:187]
	global_store_dwordx4 v[32:33], v[28:31], off
	s_waitcnt vmcnt(7)
	s_nop 0
	v_lshlrev_b32_e32 v28, 16, v102
	v_and_b32_e32 v29, 0xffff0000, v102
	v_lshlrev_b32_e32 v30, 16, v103
	v_and_b32_e32 v31, 0xffff0000, v103
	v_pk_fma_f32 v[26:27], v[26:27], v[176:177], v[30:31]
	v_pk_fma_f32 v[24:25], v[24:25], v[174:175], v[28:29]
	v_lshlrev_b32_e32 v28, 16, v104
	v_and_b32_e32 v29, 0xffff0000, v104
	v_lshlrev_b32_e32 v30, 16, v105
	v_and_b32_e32 v31, 0xffff0000, v105
	v_pk_fma_f32 v[30:31], v[22:23], v[172:173], v[30:31]
	v_pk_fma_f32 v[22:23], v[20:21], v[170:171], v[28:29]
	v_cvt_pk_bf16_f32 v20, v24, v25
	v_cvt_pk_bf16_f32 v21, v26, v27
	s_nop 0
	v_cvt_pk_bf16_f32 v22, v22, v23
	v_cvt_pk_bf16_f32 v23, v30, v31
	global_store_dwordx4 v[32:33], v[20:23], off offset:256
	s_waitcnt vmcnt(7)
	s_nop 0
	v_lshlrev_b32_e32 v20, 16, v76
	v_and_b32_e32 v21, 0xffff0000, v76
	v_lshlrev_b32_e32 v22, 16, v77
	v_and_b32_e32 v23, 0xffff0000, v77
	v_pk_fma_f32 v[18:19], v[18:19], v[184:185], v[22:23]
	v_pk_fma_f32 v[16:17], v[16:17], v[182:183], v[20:21]
	v_lshlrev_b32_e32 v20, 16, v78
	v_and_b32_e32 v21, 0xffff0000, v78
	v_lshlrev_b32_e32 v22, 16, v79
	v_and_b32_e32 v23, 0xffff0000, v79
	v_pk_fma_f32 v[22:23], v[14:15], v[180:181], v[22:23]
	v_pk_fma_f32 v[14:15], v[12:13], v[178:179], v[20:21]
	v_cvt_pk_bf16_f32 v12, v16, v17
	v_lshl_add_u64 v[16:17], s[10:11], 0, v[86:87]
	v_cvt_pk_bf16_f32 v13, v18, v19
	v_cvt_pk_bf16_f32 v14, v14, v15
	v_cvt_pk_bf16_f32 v15, v22, v23
	v_lshl_add_u64 v[16:17], v[16:17], 0, v[186:187]
	global_store_dwordx4 v[16:17], v[12:15], off
	s_waitcnt vmcnt(7)
	s_nop 0
	v_lshlrev_b32_e32 v12, 16, v68
	v_and_b32_e32 v13, 0xffff0000, v68
	v_lshlrev_b32_e32 v14, 16, v69
	v_and_b32_e32 v15, 0xffff0000, v69
	v_pk_fma_f32 v[10:11], v[10:11], v[176:177], v[14:15]
	v_pk_fma_f32 v[8:9], v[8:9], v[174:175], v[12:13]
	v_lshlrev_b32_e32 v12, 16, v70
	v_and_b32_e32 v13, 0xffff0000, v70
	v_lshlrev_b32_e32 v14, 16, v71
	v_and_b32_e32 v15, 0xffff0000, v71
	v_pk_fma_f32 v[14:15], v[6:7], v[172:173], v[14:15]
	v_pk_fma_f32 v[6:7], v[4:5], v[170:171], v[12:13]
	v_cvt_pk_bf16_f32 v4, v8, v9
	v_cvt_pk_bf16_f32 v5, v10, v11
	s_nop 0
	v_cvt_pk_bf16_f32 v6, v6, v7
	v_cvt_pk_bf16_f32 v7, v14, v15
	global_store_dwordx4 v[16:17], v[4:7], off offset:256
	s_cbranch_vccnz .LBB0_425
	s_andn2_b64 vcc, exec, s[8:9]
	s_cbranch_vccnz .LBB0_424
	s_barrier
	s_branch .LBB0_424

.LBB0_1216:
	v_lshl_or_b32 v148, s25, 8, v192
	v_lshl_add_u32 v150, s24, 8, v190
	s_lshl_b64 s[24:25], s[26:27], 2
	v_ashrrev_i32_e32 v149, 31, v148
	s_add_u32 s24, s77, s24
	v_lshlrev_b64 v[178:179], 1, v[148:149]
	v_ashrrev_i32_e32 v151, 31, v150
	s_addc_u32 s25, s78, s25
	v_lshl_add_u64 v[180:181], s[8:9], 0, v[178:179]
	v_lshlrev_b64 v[182:183], 12, v[150:151]
	v_lshl_add_u64 v[72:73], v[148:149], 2, s[24:25]
	v_lshl_add_u64 v[148:149], v[180:181], 0, v[182:183]
	s_mov_b64 vcc, 0x80000
	global_load_dwordx4 v[76:79], v[72:73], off offset:16
	global_load_dwordx4 v[80:83], v[72:73], off
	global_load_dwordx4 v[68:71], v[72:73], off offset:528
	s_nop 0
	global_load_dwordx4 v[72:75], v[72:73], off offset:512
	s_nop 0
	v_lshl_add_u64 v[250:251], v[148:149], 0, vcc
	global_load_dwordx4 v[244:247], v[250:251], off
	global_load_dwordx4 v[244:247], v[250:251], off offset:256
	global_load_dwordx4 v[200:203], v[148:149], off
	global_load_dwordx4 v[204:207], v[148:149], off offset:256
	v_or_b32_e32 v148, 16, v150
	v_ashrrev_i32_e32 v149, 31, v148
	v_lshlrev_b64 v[188:189], 12, v[148:149]
	v_lshl_add_u64 v[148:149], v[180:181], 0, v[188:189]
	v_lshl_add_u64 v[250:251], v[148:149], 0, vcc
	global_load_dwordx4 v[244:247], v[250:251], off
	global_load_dwordx4 v[244:247], v[250:251], off offset:256
	global_load_dwordx4 v[208:211], v[148:149], off
	global_load_dwordx4 v[164:167], v[148:149], off offset:256
	v_or_b32_e32 v148, 32, v150
	v_ashrrev_i32_e32 v149, 31, v148
	v_lshlrev_b64 v[186:187], 12, v[148:149]
	v_lshl_add_u64 v[148:149], v[180:181], 0, v[186:187]
	v_lshl_add_u64 v[250:251], v[148:149], 0, vcc
	global_load_dwordx4 v[244:247], v[250:251], off
	global_load_dwordx4 v[244:247], v[250:251], off offset:256
	global_load_dwordx4 v[160:163], v[148:149], off
	global_load_dwordx4 v[156:159], v[148:149], off offset:256
	v_or_b32_e32 v148, 48, v150
	v_ashrrev_i32_e32 v149, 31, v148
	v_lshlrev_b64 v[184:185], 12, v[148:149]
	v_lshl_add_u64 v[148:149], v[180:181], 0, v[184:185]
	v_lshl_add_u64 v[250:251], v[148:149], 0, vcc
	global_load_dwordx4 v[244:247], v[250:251], off
	global_load_dwordx4 v[244:247], v[250:251], off offset:256
	global_load_dwordx4 v[152:155], v[148:149], off
	s_nop 0
	global_load_dwordx4 v[148:151], v[148:149], off offset:256
	s_mov_b64 s[24:25], 0x80000
	s_andn2_b64 vcc, exec, s[4:5]
	s_waitcnt vmcnt(0)
	v_lshlrev_b32_e32 v194, 16, v200
	v_and_b32_e32 v195, 0xffff0000, v200
	v_lshlrev_b32_e32 v198, 16, v201
	v_and_b32_e32 v199, 0xffff0000, v201
	v_pk_fma_f32 v[146:147], v[146:147], v[82:83], v[198:199]
	v_pk_fma_f32 v[144:145], v[144:145], v[80:81], v[194:195]
	v_lshlrev_b32_e32 v194, 16, v202
	v_and_b32_e32 v195, 0xffff0000, v202
	v_lshlrev_b32_e32 v198, 16, v203
	v_and_b32_e32 v199, 0xffff0000, v203
	v_pk_fma_f32 v[198:199], v[142:143], v[78:79], v[198:199]
	v_pk_fma_f32 v[142:143], v[140:141], v[76:77], v[194:195]
	v_cvt_pk_bf16_f32 v140, v144, v145
	v_lshl_add_u64 v[144:145], s[8:9], 0, v[182:183]
	v_cvt_pk_bf16_f32 v141, v146, v147
	v_cvt_pk_bf16_f32 v142, v142, v143
	v_cvt_pk_bf16_f32 v143, v198, v199
	v_lshl_add_u64 v[144:145], v[144:145], 0, v[178:179]
	global_store_dwordx4 v[144:145], v[140:143], off
	s_nop 1
	v_lshlrev_b32_e32 v140, 16, v204
	v_and_b32_e32 v141, 0xffff0000, v204
	v_lshlrev_b32_e32 v142, 16, v205
	v_and_b32_e32 v143, 0xffff0000, v205
	v_pk_fma_f32 v[134:135], v[134:135], v[74:75], v[142:143]
	v_pk_fma_f32 v[132:133], v[132:133], v[72:73], v[140:141]
	v_lshlrev_b32_e32 v140, 16, v206
	v_and_b32_e32 v141, 0xffff0000, v206
	v_lshlrev_b32_e32 v142, 16, v207
	v_and_b32_e32 v143, 0xffff0000, v207
	v_pk_fma_f32 v[142:143], v[126:127], v[70:71], v[142:143]
	v_pk_fma_f32 v[126:127], v[124:125], v[68:69], v[140:141]
	v_cvt_pk_bf16_f32 v124, v132, v133
	v_cvt_pk_bf16_f32 v125, v134, v135
	v_lshlrev_b32_e32 v132, 16, v210
	v_cvt_pk_bf16_f32 v126, v126, v127
	v_cvt_pk_bf16_f32 v127, v142, v143
	global_store_dwordx4 v[144:145], v[124:127], off offset:256
	v_and_b32_e32 v133, 0xffff0000, v210
	v_pk_fma_f32 v[128:129], v[128:129], v[76:77], v[132:133]
	v_lshlrev_b32_e32 v124, 16, v208
	v_and_b32_e32 v125, 0xffff0000, v208
	v_lshlrev_b32_e32 v126, 16, v209
	v_and_b32_e32 v127, 0xffff0000, v209
	v_pk_fma_f32 v[126:127], v[138:139], v[82:83], v[126:127]
	v_pk_fma_f32 v[124:125], v[136:137], v[80:81], v[124:125]
	v_lshlrev_b32_e32 v134, 16, v211
	v_and_b32_e32 v135, 0xffff0000, v211
	v_cvt_pk_bf16_f32 v124, v124, v125
	v_cvt_pk_bf16_f32 v125, v126, v127
	v_cvt_pk_bf16_f32 v126, v128, v129
	v_lshl_add_u64 v[128:129], s[8:9], 0, v[188:189]
	v_pk_fma_f32 v[130:131], v[130:131], v[78:79], v[134:135]
	v_lshl_add_u64 v[128:129], v[128:129], 0, v[178:179]
	v_cvt_pk_bf16_f32 v127, v130, v131
	global_store_dwordx4 v[128:129], v[124:127], off
	s_nop 1
	v_lshlrev_b32_e32 v124, 16, v164
	v_and_b32_e32 v125, 0xffff0000, v164
	v_lshlrev_b32_e32 v126, 16, v165
	v_and_b32_e32 v127, 0xffff0000, v165
	v_pk_fma_f32 v[122:123], v[122:123], v[74:75], v[126:127]
	v_pk_fma_f32 v[120:121], v[120:121], v[72:73], v[124:125]
	v_lshlrev_b32_e32 v124, 16, v166
	v_and_b32_e32 v125, 0xffff0000, v166
	v_lshlrev_b32_e32 v126, 16, v167
	v_and_b32_e32 v127, 0xffff0000, v167
	v_pk_fma_f32 v[126:127], v[118:119], v[70:71], v[126:127]
	v_pk_fma_f32 v[118:119], v[116:117], v[68:69], v[124:125]
	v_cvt_pk_bf16_f32 v116, v120, v121
	v_cvt_pk_bf16_f32 v117, v122, v123
	s_nop 0
	v_cvt_pk_bf16_f32 v118, v118, v119
	v_cvt_pk_bf16_f32 v119, v126, v127
	global_store_dwordx4 v[128:129], v[116:119], off offset:256
	s_nop 1
	v_lshlrev_b32_e32 v116, 16, v160
	v_and_b32_e32 v117, 0xffff0000, v160
	v_lshlrev_b32_e32 v118, 16, v161
	v_and_b32_e32 v119, 0xffff0000, v161
	v_pk_fma_f32 v[114:115], v[114:115], v[82:83], v[118:119]
	v_pk_fma_f32 v[112:113], v[112:113], v[80:81], v[116:117]
	v_lshlrev_b32_e32 v116, 16, v162
	v_and_b32_e32 v117, 0xffff0000, v162
	v_lshlrev_b32_e32 v118, 16, v163
	v_and_b32_e32 v119, 0xffff0000, v163
	v_pk_fma_f32 v[118:119], v[110:111], v[78:79], v[118:119]
	v_pk_fma_f32 v[110:111], v[108:109], v[76:77], v[116:117]
	v_cvt_pk_bf16_f32 v108, v112, v113
	v_lshl_add_u64 v[112:113], s[8:9], 0, v[186:187]
	v_cvt_pk_bf16_f32 v109, v114, v115
	v_cvt_pk_bf16_f32 v110, v110, v111
	v_cvt_pk_bf16_f32 v111, v118, v119
	v_lshl_add_u64 v[112:113], v[112:113], 0, v[178:179]
	global_store_dwordx4 v[112:113], v[108:111], off
	s_nop 1
	v_lshlrev_b32_e32 v108, 16, v156
	v_and_b32_e32 v109, 0xffff0000, v156
	v_lshlrev_b32_e32 v110, 16, v157
	v_and_b32_e32 v111, 0xffff0000, v157
	v_pk_fma_f32 v[102:103], v[102:103], v[74:75], v[110:111]
	v_pk_fma_f32 v[100:101], v[100:101], v[72:73], v[108:109]
	v_lshlrev_b32_e32 v108, 16, v158
	v_and_b32_e32 v109, 0xffff0000, v158
	v_lshlrev_b32_e32 v110, 16, v159
	v_and_b32_e32 v111, 0xffff0000, v159
	v_pk_fma_f32 v[110:111], v[94:95], v[70:71], v[110:111]
	v_pk_fma_f32 v[94:95], v[92:93], v[68:69], v[108:109]
	v_cvt_pk_bf16_f32 v92, v100, v101
	v_cvt_pk_bf16_f32 v93, v102, v103
	v_lshlrev_b32_e32 v100, 16, v154
	v_cvt_pk_bf16_f32 v94, v94, v95
	v_cvt_pk_bf16_f32 v95, v110, v111
	global_store_dwordx4 v[112:113], v[92:95], off offset:256
	v_and_b32_e32 v101, 0xffff0000, v154
	v_pk_fma_f32 v[96:97], v[96:97], v[76:77], v[100:101]
	v_lshlrev_b32_e32 v92, 16, v152
	v_and_b32_e32 v93, 0xffff0000, v152
	v_lshlrev_b32_e32 v94, 16, v153
	v_and_b32_e32 v95, 0xffff0000, v153
	v_pk_fma_f32 v[94:95], v[106:107], v[82:83], v[94:95]
	v_pk_fma_f32 v[92:93], v[104:105], v[80:81], v[92:93]
	v_lshlrev_b32_e32 v102, 16, v155
	v_and_b32_e32 v103, 0xffff0000, v155
	v_cvt_pk_bf16_f32 v92, v92, v93
	v_cvt_pk_bf16_f32 v93, v94, v95
	v_cvt_pk_bf16_f32 v94, v96, v97
	v_lshl_add_u64 v[96:97], s[8:9], 0, v[184:185]
	v_pk_fma_f32 v[98:99], v[98:99], v[78:79], v[102:103]
	v_lshl_add_u64 v[96:97], v[96:97], 0, v[178:179]
	v_cvt_pk_bf16_f32 v95, v98, v99
	global_store_dwordx4 v[96:97], v[92:95], off
	v_lshl_add_u64 v[100:101], v[182:183], 0, s[24:25]
	s_mov_b64 s[24:25], 0x90000
	v_lshlrev_b32_e32 v92, 16, v148
	v_and_b32_e32 v93, 0xffff0000, v148
	v_lshlrev_b32_e32 v94, 16, v149
	v_and_b32_e32 v95, 0xffff0000, v149
	v_pk_fma_f32 v[90:91], v[90:91], v[74:75], v[94:95]
	v_pk_fma_f32 v[88:89], v[88:89], v[72:73], v[92:93]
	v_lshlrev_b32_e32 v92, 16, v150
	v_and_b32_e32 v93, 0xffff0000, v150
	v_lshlrev_b32_e32 v94, 16, v151
	v_and_b32_e32 v95, 0xffff0000, v151
	v_pk_fma_f32 v[94:95], v[86:87], v[70:71], v[94:95]
	v_pk_fma_f32 v[86:87], v[84:85], v[68:69], v[92:93]
	v_cvt_pk_bf16_f32 v84, v88, v89
	v_cvt_pk_bf16_f32 v85, v90, v91
	v_lshl_add_u64 v[104:105], v[182:183], 0, s[24:25]
	v_cvt_pk_bf16_f32 v86, v86, v87
	v_cvt_pk_bf16_f32 v87, v94, v95
	global_store_dwordx4 v[96:97], v[84:87], off offset:256
	s_mov_b64 s[24:25], 0xa0000
	v_lshl_add_u64 v[122:123], v[182:183], 0, s[24:25]
	v_lshl_add_u64 v[84:85], v[180:181], 0, v[100:101]
	global_load_dwordx4 v[88:91], v[84:85], off
	global_load_dwordx4 v[96:99], v[84:85], off offset:256
	v_lshl_add_u64 v[84:85], v[180:181], 0, v[104:105]
	global_load_dwordx4 v[106:109], v[84:85], off
	global_load_dwordx4 v[110:113], v[84:85], off offset:256
	v_lshl_add_u64 v[84:85], v[180:181], 0, v[122:123]
	global_load_dwordx4 v[114:117], v[84:85], off
	global_load_dwordx4 v[118:121], v[84:85], off offset:256
	s_mov_b64 s[24:25], 0xb0000
	v_lshl_add_u64 v[102:103], v[182:183], 0, s[24:25]
	v_lshl_add_u64 v[84:85], v[180:181], 0, v[102:103]
	global_load_dwordx4 v[92:95], v[84:85], off
	s_nop 0
	global_load_dwordx4 v[84:87], v[84:85], off offset:256
	s_mov_b64 s[24:25], -1
	s_waitcnt vmcnt(7)
	v_lshlrev_b32_e32 v124, 16, v88
	v_and_b32_e32 v125, 0xffff0000, v88
	v_lshlrev_b32_e32 v88, 16, v89
	v_and_b32_e32 v89, 0xffff0000, v89
	v_pk_fma_f32 v[66:67], v[66:67], v[82:83], v[88:89]
	v_pk_fma_f32 v[64:65], v[64:65], v[80:81], v[124:125]
	v_lshlrev_b32_e32 v88, 16, v90
	v_and_b32_e32 v89, 0xffff0000, v90
	v_lshlrev_b32_e32 v90, 16, v91
	v_and_b32_e32 v91, 0xffff0000, v91
	v_pk_fma_f32 v[90:91], v[62:63], v[78:79], v[90:91]
	v_pk_fma_f32 v[62:63], v[60:61], v[76:77], v[88:89]
	v_cvt_pk_bf16_f32 v60, v64, v65
	v_lshl_add_u64 v[64:65], s[8:9], 0, v[100:101]
	v_cvt_pk_bf16_f32 v61, v66, v67
	v_cvt_pk_bf16_f32 v62, v62, v63
	v_cvt_pk_bf16_f32 v63, v90, v91
	v_lshl_add_u64 v[64:65], v[64:65], 0, v[178:179]
	global_store_dwordx4 v[64:65], v[60:63], off
	s_waitcnt vmcnt(7)
	s_nop 0
	v_lshlrev_b32_e32 v60, 16, v96
	v_and_b32_e32 v61, 0xffff0000, v96
	v_lshlrev_b32_e32 v62, 16, v97
	v_and_b32_e32 v63, 0xffff0000, v97
	v_pk_fma_f32 v[58:59], v[58:59], v[74:75], v[62:63]
	v_pk_fma_f32 v[56:57], v[56:57], v[72:73], v[60:61]
	v_lshlrev_b32_e32 v60, 16, v98
	v_and_b32_e32 v61, 0xffff0000, v98
	v_lshlrev_b32_e32 v62, 16, v99
	v_and_b32_e32 v63, 0xffff0000, v99
	v_pk_fma_f32 v[62:63], v[54:55], v[70:71], v[62:63]
	v_pk_fma_f32 v[54:55], v[52:53], v[68:69], v[60:61]
	v_cvt_pk_bf16_f32 v52, v56, v57
	v_cvt_pk_bf16_f32 v53, v58, v59
	s_nop 0
	v_cvt_pk_bf16_f32 v54, v54, v55
	v_cvt_pk_bf16_f32 v55, v62, v63
	global_store_dwordx4 v[64:65], v[52:55], off offset:256
	s_waitcnt vmcnt(7)
	s_nop 0
	v_lshlrev_b32_e32 v52, 16, v106
	v_and_b32_e32 v53, 0xffff0000, v106
	v_lshlrev_b32_e32 v54, 16, v107
	v_and_b32_e32 v55, 0xffff0000, v107
	v_pk_fma_f32 v[50:51], v[50:51], v[82:83], v[54:55]
	v_pk_fma_f32 v[48:49], v[48:49], v[80:81], v[52:53]
	v_lshlrev_b32_e32 v52, 16, v108
	v_and_b32_e32 v53, 0xffff0000, v108
	v_lshlrev_b32_e32 v54, 16, v109
	v_and_b32_e32 v55, 0xffff0000, v109
	v_pk_fma_f32 v[54:55], v[46:47], v[78:79], v[54:55]
	v_pk_fma_f32 v[46:47], v[44:45], v[76:77], v[52:53]
	v_cvt_pk_bf16_f32 v44, v48, v49
	v_lshl_add_u64 v[48:49], s[8:9], 0, v[104:105]
	v_cvt_pk_bf16_f32 v45, v50, v51
	v_cvt_pk_bf16_f32 v46, v46, v47
	v_cvt_pk_bf16_f32 v47, v54, v55
	v_lshl_add_u64 v[48:49], v[48:49], 0, v[178:179]
	global_store_dwordx4 v[48:49], v[44:47], off
	s_waitcnt vmcnt(7)
	s_nop 0
	v_lshlrev_b32_e32 v44, 16, v110
	v_and_b32_e32 v45, 0xffff0000, v110
	v_lshlrev_b32_e32 v46, 16, v111
	v_and_b32_e32 v47, 0xffff0000, v111
	v_pk_fma_f32 v[42:43], v[42:43], v[74:75], v[46:47]
	v_pk_fma_f32 v[40:41], v[40:41], v[72:73], v[44:45]
	v_lshlrev_b32_e32 v44, 16, v112
	v_and_b32_e32 v45, 0xffff0000, v112
	v_lshlrev_b32_e32 v46, 16, v113
	v_and_b32_e32 v47, 0xffff0000, v113
	v_pk_fma_f32 v[46:47], v[38:39], v[70:71], v[46:47]
	v_pk_fma_f32 v[38:39], v[36:37], v[68:69], v[44:45]
	v_cvt_pk_bf16_f32 v36, v40, v41
	v_cvt_pk_bf16_f32 v37, v42, v43
	s_nop 0
	v_cvt_pk_bf16_f32 v38, v38, v39
	v_cvt_pk_bf16_f32 v39, v46, v47
	global_store_dwordx4 v[48:49], v[36:39], off offset:256
	s_waitcnt vmcnt(7)
	s_nop 0
	v_lshlrev_b32_e32 v36, 16, v114
	v_and_b32_e32 v37, 0xffff0000, v114
	v_lshlrev_b32_e32 v38, 16, v115
	v_and_b32_e32 v39, 0xffff0000, v115
	v_pk_fma_f32 v[34:35], v[34:35], v[82:83], v[38:39]
	v_pk_fma_f32 v[32:33], v[32:33], v[80:81], v[36:37]
	v_lshlrev_b32_e32 v36, 16, v116
	v_and_b32_e32 v37, 0xffff0000, v116
	v_lshlrev_b32_e32 v38, 16, v117
	v_and_b32_e32 v39, 0xffff0000, v117
	v_pk_fma_f32 v[38:39], v[30:31], v[78:79], v[38:39]
	v_pk_fma_f32 v[30:31], v[28:29], v[76:77], v[36:37]
	v_cvt_pk_bf16_f32 v28, v32, v33
	v_lshl_add_u64 v[32:33], s[8:9], 0, v[122:123]
	v_cvt_pk_bf16_f32 v29, v34, v35
	v_cvt_pk_bf16_f32 v30, v30, v31
	v_cvt_pk_bf16_f32 v31, v38, v39
	v_lshl_add_u64 v[32:33], v[32:33], 0, v[178:179]
	global_store_dwordx4 v[32:33], v[28:31], off
	s_waitcnt vmcnt(7)
	s_nop 0
	v_lshlrev_b32_e32 v28, 16, v118
	v_and_b32_e32 v29, 0xffff0000, v118
	v_lshlrev_b32_e32 v30, 16, v119
	v_and_b32_e32 v31, 0xffff0000, v119
	v_pk_fma_f32 v[26:27], v[26:27], v[74:75], v[30:31]
	v_pk_fma_f32 v[24:25], v[24:25], v[72:73], v[28:29]
	v_lshlrev_b32_e32 v28, 16, v120
	v_and_b32_e32 v29, 0xffff0000, v120
	v_lshlrev_b32_e32 v30, 16, v121
	v_and_b32_e32 v31, 0xffff0000, v121
	v_pk_fma_f32 v[30:31], v[22:23], v[70:71], v[30:31]
	v_pk_fma_f32 v[22:23], v[20:21], v[68:69], v[28:29]
	v_cvt_pk_bf16_f32 v20, v24, v25
	v_cvt_pk_bf16_f32 v21, v26, v27
	s_nop 0
	v_cvt_pk_bf16_f32 v22, v22, v23
	v_cvt_pk_bf16_f32 v23, v30, v31
	global_store_dwordx4 v[32:33], v[20:23], off offset:256
	s_waitcnt vmcnt(7)
	s_nop 0
	v_lshlrev_b32_e32 v20, 16, v92
	v_and_b32_e32 v21, 0xffff0000, v92
	v_lshlrev_b32_e32 v22, 16, v93
	v_and_b32_e32 v23, 0xffff0000, v93
	v_pk_fma_f32 v[18:19], v[18:19], v[82:83], v[22:23]
	v_pk_fma_f32 v[16:17], v[16:17], v[80:81], v[20:21]
	v_lshlrev_b32_e32 v20, 16, v94
	v_and_b32_e32 v21, 0xffff0000, v94
	v_lshlrev_b32_e32 v22, 16, v95
	v_and_b32_e32 v23, 0xffff0000, v95
	v_pk_fma_f32 v[22:23], v[14:15], v[78:79], v[22:23]
	v_pk_fma_f32 v[14:15], v[12:13], v[76:77], v[20:21]
	v_cvt_pk_bf16_f32 v12, v16, v17
	v_lshl_add_u64 v[16:17], s[8:9], 0, v[102:103]
	v_cvt_pk_bf16_f32 v13, v18, v19
	v_cvt_pk_bf16_f32 v14, v14, v15
	v_cvt_pk_bf16_f32 v15, v22, v23
	v_lshl_add_u64 v[16:17], v[16:17], 0, v[178:179]
	global_store_dwordx4 v[16:17], v[12:15], off
	s_waitcnt vmcnt(7)
	s_nop 0
	v_lshlrev_b32_e32 v12, 16, v84
	v_and_b32_e32 v13, 0xffff0000, v84
	v_lshlrev_b32_e32 v14, 16, v85
	v_and_b32_e32 v15, 0xffff0000, v85
	v_pk_fma_f32 v[10:11], v[10:11], v[74:75], v[14:15]
	v_pk_fma_f32 v[8:9], v[8:9], v[72:73], v[12:13]
	v_lshlrev_b32_e32 v12, 16, v86
	v_and_b32_e32 v13, 0xffff0000, v86
	v_lshlrev_b32_e32 v14, 16, v87
	v_and_b32_e32 v15, 0xffff0000, v87
	v_pk_fma_f32 v[14:15], v[6:7], v[70:71], v[14:15]
	v_pk_fma_f32 v[6:7], v[4:5], v[68:69], v[12:13]
	v_cvt_pk_bf16_f32 v4, v8, v9
	v_cvt_pk_bf16_f32 v5, v10, v11
	s_nop 0
	v_cvt_pk_bf16_f32 v6, v6, v7
	v_cvt_pk_bf16_f32 v7, v14, v15
	global_store_dwordx4 v[16:17], v[4:7], off offset:256
	s_cbranch_vccnz .LBB0_1203
	s_andn2_b64 vcc, exec, s[6:7]
	s_cbranch_vccnz .LBB0_1202
	s_barrier
	s_branch .LBB0_1202
